# all four 256x128 GEMM K-loops re-scheduled: 2 LDS stages, one barrier per K-step, MFMAs interleaved with LDS writes/reads and next-tile loads
# speedup vs baseline: 1.0364x; 1.0206x over previous
; #define MFMA(a, b, c) __builtin_amdgcn_mfma_f32_32x32x16_f16(__builtin_bit_cast(h16x8, (a)), __builtin_bit_cast(h16x8, (b)), (c), 0, 0, 0)
; template <int MODE, bool BIG = false> DI void gemm_tile(const Params& p, int tm, int tn, int kv, char* smem) {
;     ...
;     char* Bs2 = smem + 256 * 80;
;     uint4 ra[4], rb[2];
; #pragma unroll
;     for (int i = 0; i < 4; ++i) { const int id = tid + 256 * i; ra[i] = load_a<MODE>(p, tma, kv, id >> 2, 0, id & 3); }
; #pragma unroll
;     for (int i = 0; i < 2; ++i) { const int id = tid + 256 * i; rb[i] = load_b<MODE>(p, tn, kv, id >> 2, 0, id & 3); }
;     for (int kt = 0; kt < 2 * KT; ++kt) {
;       __syncthreads();
; #pragma unroll
;       for (int i = 0; i < 4; ++i) { const int id = tid + 256 * i; *(uint4*)(As + (id >> 2) * 80 + (id & 3) * 16) = ra[i]; }
; #pragma unroll
;       for (int i = 0; i < 2; ++i) { const int id = tid + 256 * i; *(uint4*)(Bs2 + (id >> 2) * 80 + (id & 3) * 16) = rb[i]; }
;       __syncthreads();
;       if (kt + 1 < 2 * KT) {
;         const int k1 = kt + 1;
; #pragma unroll
;         for (int i = 0; i < 4; ++i) { const int id = tid + 256 * i; ra[i] = load_a<MODE>(p, tma, kv, id >> 2, k1 >> 1, ((k1 & 1) << 2) | (id & 3)); }
; #pragma unroll
;         for (int i = 0; i < 2; ++i) { const int id = tid + 256 * i; rb[i] = load_b<MODE>(p, tn, kv, id >> 2, k1 >> 1, ((k1 & 1) << 2) | (id & 3)); }
;       }
;       {
;         bf16x8 af[2][4], bfr[2][2];
; #pragma unroll
;         for (int s = 0; s < 2; ++s) {
; #pragma unroll
;           for (int i = 0; i < 4; ++i) af[s][i] = *(const bf16x8*)(As + (wm * 128 + i * 32 + r) * 80 + s * 32 + hf * 16);
; #pragma unroll
;           for (int j = 0; j < 2; ++j) bfr[s][j] = *(const bf16x8*)(Bs2 + (wn * 64 + j * 32 + r) * 80 + s * 32 + hf * 16);
;         }
;         __builtin_amdgcn_s_setprio(1);
; #pragma unroll
;         for (int s = 0; s < 2; ++s)
; #pragma unroll
;           for (int i = 0; i < 4; ++i)
; #pragma unroll
;             for (int j = 0; j < 2; ++j) acc[i][j] = MFMA(af[s][i], bfr[s][j], acc[i][j]);
;         __builtin_amdgcn_s_setprio(0);
;       }
;     }
.LBB0_121:
	s_barrier
	s_waitcnt vmcnt(5)
	ds_write_b128 v181, v[132:135]
	s_waitcnt vmcnt(4)
	ds_write_b128 v180, v[128:131]
	s_waitcnt vmcnt(3)
	ds_write_b128 v183, v[140:143]
	s_waitcnt vmcnt(2)
	ds_write_b128 v182, v[136:139]
	s_waitcnt vmcnt(1)
	ds_write_b128 v181, v[148:151] offset:20480
	s_waitcnt vmcnt(0)
	ds_write_b128 v180, v[144:147] offset:20480
	s_and_b32 s8, s7, 0x7c0
	s_lshl_b32 s10, s8, 1
	v_and_or_b32 v128, s6, 4, v184
	s_add_u32 s8, s2, s10
	v_lshlrev_b32_e32 v154, 4, v128
	s_addc_u32 s9, s3, 0
	v_lshl_add_u64 v[128:129], s[8:9], 0, v[154:155]
	s_add_u32 s8, s94, s10
	v_lshl_add_u64 v[130:131], v[128:129], 0, v[156:157]
	v_lshl_add_u64 v[136:137], v[128:129], 0, v[158:159]
	v_lshl_add_u64 v[138:139], v[128:129], 0, v[160:161]
	v_lshl_add_u64 v[144:145], v[128:129], 0, v[162:163]
	s_addc_u32 s9, s95, 0
	global_load_dwordx4 v[132:135], v[130:131], off
	s_nop 0
	global_load_dwordx4 v[128:131], v[136:137], off
	global_load_dwordx4 v[140:143], v[138:139], off
	s_nop 0
	global_load_dwordx4 v[136:139], v[144:145], off
	v_lshl_add_u64 v[144:145], s[8:9], 0, v[154:155]
	v_lshl_add_u64 v[146:147], v[144:145], 0, v[168:169]
	v_lshl_add_u64 v[144:145], v[144:145], 0, v[170:171]
	global_load_dwordx4 v[148:151], v[146:147], off
	s_nop 0
	global_load_dwordx4 v[144:147], v[144:145], off
	s_add_i32 s6, s6, 4
	s_add_i32 s7, s7, 32
	s_waitcnt lgkmcnt(0)
	s_barrier
	ds_read_b128 v[186:189], v176
	ds_read_b128 v[194:197], v176 offset:2560
	ds_read_b128 v[206:209], v176 offset:5120
	ds_read_b128 v[214:217], v179
	ds_read_b128 v[222:225], v178 offset:20480
	ds_read_b128 v[230:233], v178 offset:23040
.Lgk_inproj_loop:
	ds_read_b128 v[190:193], v176 offset:32
	ds_read_b128 v[198:201], v176 offset:2592
	ds_read_b128 v[210:213], v176 offset:5152
	ds_read_b128 v[218:221], v179 offset:32
	ds_read_b128 v[226:229], v178 offset:20512
	ds_read_b128 v[234:237], v178 offset:23072
	s_setprio 1
	s_waitcnt lgkmcnt(6)
	v_mfma_f32_32x32x16_f16 v[112:127], v[186:189], v[222:225], v[112:127]
	s_waitcnt vmcnt(5)
	ds_write_b128 v181, v[132:135] offset:32768
	v_mfma_f32_32x32x16_f16 v[96:111], v[186:189], v[230:233], v[96:111]
	s_waitcnt vmcnt(4)
	ds_write_b128 v180, v[128:131] offset:32768
	v_mfma_f32_32x32x16_f16 v[80:95], v[194:197], v[222:225], v[80:95]
	s_waitcnt vmcnt(3)
	ds_write_b128 v183, v[140:143] offset:32768
	v_mfma_f32_32x32x16_f16 v[64:79], v[194:197], v[230:233], v[64:79]
	s_waitcnt vmcnt(2)
	ds_write_b128 v182, v[136:139] offset:32768
	v_mfma_f32_32x32x16_f16 v[48:63], v[206:209], v[222:225], v[48:63]
	s_waitcnt vmcnt(1)
	ds_write_b128 v181, v[148:151] offset:53248
	v_mfma_f32_32x32x16_f16 v[32:47], v[206:209], v[230:233], v[32:47]
	s_waitcnt vmcnt(0)
	ds_write_b128 v180, v[144:147] offset:53248
	v_mfma_f32_32x32x16_f16 v[16:31], v[214:217], v[222:225], v[16:31]
	s_and_b32 s8, s7, 0x7c0
	s_lshl_b32 s10, s8, 1
	v_and_or_b32 v128, s6, 4, v184
	s_add_u32 s8, s2, s10
	v_lshlrev_b32_e32 v154, 4, v128
	s_addc_u32 s9, s3, 0
	v_lshl_add_u64 v[128:129], s[8:9], 0, v[154:155]
	s_add_u32 s8, s94, s10
	v_lshl_add_u64 v[130:131], v[128:129], 0, v[156:157]
	v_lshl_add_u64 v[136:137], v[128:129], 0, v[158:159]
	v_mfma_f32_32x32x16_f16 v[0:15], v[214:217], v[230:233], v[0:15]
	v_lshl_add_u64 v[138:139], v[128:129], 0, v[160:161]
	v_lshl_add_u64 v[144:145], v[128:129], 0, v[162:163]
	s_addc_u32 s9, s95, 0
	global_load_dwordx4 v[132:135], v[130:131], off
	s_nop 0
	global_load_dwordx4 v[128:131], v[136:137], off
	global_load_dwordx4 v[140:143], v[138:139], off
	s_nop 0
	global_load_dwordx4 v[136:139], v[144:145], off
	v_lshl_add_u64 v[144:145], s[8:9], 0, v[154:155]
	v_lshl_add_u64 v[146:147], v[144:145], 0, v[168:169]
	v_lshl_add_u64 v[144:145], v[144:145], 0, v[170:171]
	global_load_dwordx4 v[148:151], v[146:147], off
	s_nop 0
	global_load_dwordx4 v[144:147], v[144:145], off
	s_add_i32 s6, s6, 4
	s_add_i32 s7, s7, 32
	s_waitcnt lgkmcnt(0)
	s_barrier
	ds_read_b128 v[186:189], v176 offset:32768
	ds_read_b128 v[194:197], v176 offset:35328
	ds_read_b128 v[206:209], v176 offset:37888
	ds_read_b128 v[214:217], v179 offset:32768
	ds_read_b128 v[222:225], v178 offset:53248
	ds_read_b128 v[230:233], v178 offset:55808
	v_mfma_f32_32x32x16_f16 v[112:127], v[190:193], v[226:229], v[112:127]
	v_mfma_f32_32x32x16_f16 v[96:111], v[190:193], v[234:237], v[96:111]
	v_mfma_f32_32x32x16_f16 v[80:95], v[198:201], v[226:229], v[80:95]
	v_mfma_f32_32x32x16_f16 v[64:79], v[198:201], v[234:237], v[64:79]
	v_mfma_f32_32x32x16_f16 v[48:63], v[210:213], v[226:229], v[48:63]
	v_mfma_f32_32x32x16_f16 v[32:47], v[210:213], v[234:237], v[32:47]
	v_mfma_f32_32x32x16_f16 v[16:31], v[218:221], v[226:229], v[16:31]
	v_mfma_f32_32x32x16_f16 v[0:15], v[218:221], v[234:237], v[0:15]
	s_setprio 0
	ds_read_b128 v[190:193], v176 offset:32800
	ds_read_b128 v[198:201], v176 offset:35360
	ds_read_b128 v[210:213], v176 offset:37920
	ds_read_b128 v[218:221], v179 offset:32800
	ds_read_b128 v[226:229], v178 offset:53280
	ds_read_b128 v[234:237], v178 offset:55840
	s_setprio 1
	s_waitcnt lgkmcnt(6)
	v_mfma_f32_32x32x16_f16 v[112:127], v[186:189], v[222:225], v[112:127]
	s_waitcnt vmcnt(5)
	ds_write_b128 v181, v[132:135]
	v_mfma_f32_32x32x16_f16 v[96:111], v[186:189], v[230:233], v[96:111]
	s_waitcnt vmcnt(4)
	ds_write_b128 v180, v[128:131]
	v_mfma_f32_32x32x16_f16 v[80:95], v[194:197], v[222:225], v[80:95]
	s_waitcnt vmcnt(3)
	ds_write_b128 v183, v[140:143]
	v_mfma_f32_32x32x16_f16 v[64:79], v[194:197], v[230:233], v[64:79]
	s_waitcnt vmcnt(2)
	ds_write_b128 v182, v[136:139]
	v_mfma_f32_32x32x16_f16 v[48:63], v[206:209], v[222:225], v[48:63]
	s_waitcnt vmcnt(1)
	ds_write_b128 v181, v[148:151] offset:20480
	v_mfma_f32_32x32x16_f16 v[32:47], v[206:209], v[230:233], v[32:47]
	s_waitcnt vmcnt(0)
	ds_write_b128 v180, v[144:147] offset:20480
	v_mfma_f32_32x32x16_f16 v[16:31], v[214:217], v[222:225], v[16:31]
	s_and_b32 s8, s7, 0x7c0
	s_lshl_b32 s10, s8, 1
	v_and_or_b32 v128, s6, 4, v184
	s_add_u32 s8, s2, s10
	v_lshlrev_b32_e32 v154, 4, v128
	s_addc_u32 s9, s3, 0
	v_lshl_add_u64 v[128:129], s[8:9], 0, v[154:155]
	s_add_u32 s8, s94, s10
	v_lshl_add_u64 v[130:131], v[128:129], 0, v[156:157]
	v_lshl_add_u64 v[136:137], v[128:129], 0, v[158:159]
	v_mfma_f32_32x32x16_f16 v[0:15], v[214:217], v[230:233], v[0:15]
	v_lshl_add_u64 v[138:139], v[128:129], 0, v[160:161]
	v_lshl_add_u64 v[144:145], v[128:129], 0, v[162:163]
	s_addc_u32 s9, s95, 0
	global_load_dwordx4 v[132:135], v[130:131], off
	s_nop 0
	global_load_dwordx4 v[128:131], v[136:137], off
	global_load_dwordx4 v[140:143], v[138:139], off
	s_nop 0
	global_load_dwordx4 v[136:139], v[144:145], off
	v_lshl_add_u64 v[144:145], s[8:9], 0, v[154:155]
	v_lshl_add_u64 v[146:147], v[144:145], 0, v[168:169]
	v_lshl_add_u64 v[144:145], v[144:145], 0, v[170:171]
	global_load_dwordx4 v[148:151], v[146:147], off
	s_nop 0
	global_load_dwordx4 v[144:147], v[144:145], off
	s_add_i32 s6, s6, 4
	s_add_i32 s7, s7, 32
	s_waitcnt lgkmcnt(0)
	s_barrier
; #define MFMA(a, b, c) __builtin_amdgcn_mfma_f32_32x32x16_f16(__builtin_bit_cast(h16x8, (a)), __builtin_bit_cast(h16x8, (b)), (c), 0, 0, 0)
; template <int MODE, bool BIG = false> DI void gemm_tile(const Params& p, int tm, int tn, int kv, char* smem) {
;     ...
;     for (int kt = 0; kt < 2 * KT; ++kt) {
;       __syncthreads();
; #pragma unroll
;       for (int i = 0; i < 4; ++i) { const int id = tid + 256 * i; *(uint4*)(As + (id >> 2) * 80 + (id & 3) * 16) = ra[i]; }
; #pragma unroll
;       for (int i = 0; i < 2; ++i) { const int id = tid + 256 * i; *(uint4*)(Bs2 + (id >> 2) * 80 + (id & 3) * 16) = rb[i]; }
;       __syncthreads();
;       if (kt + 1 < 2 * KT) {
;         const int k1 = kt + 1;
; #pragma unroll
;         for (int i = 0; i < 4; ++i) { const int id = tid + 256 * i; ra[i] = load_a<MODE>(p, tma, kv, id >> 2, k1 >> 1, ((k1 & 1) << 2) | (id & 3)); }
; #pragma unroll
;         for (int i = 0; i < 2; ++i) { const int id = tid + 256 * i; rb[i] = load_b<MODE>(p, tn, kv, id >> 2, k1 >> 1, ((k1 & 1) << 2) | (id & 3)); }
;       }
;       {
;         bf16x8 af[2][4], bfr[2][2];
; #pragma unroll
;         for (int s = 0; s < 2; ++s) {
; #pragma unroll
;           for (int i = 0; i < 4; ++i) af[s][i] = *(const bf16x8*)(As + (wm * 128 + i * 32 + r) * 80 + s * 32 + hf * 16);
; #pragma unroll
;           for (int j = 0; j < 2; ++j) bfr[s][j] = *(const bf16x8*)(Bs2 + (wn * 64 + j * 32 + r) * 80 + s * 32 + hf * 16);
;         }
;         __builtin_amdgcn_s_setprio(1);
; #pragma unroll
;         for (int s = 0; s < 2; ++s)
; #pragma unroll
;           for (int i = 0; i < 4; ++i)
; #pragma unroll
;             for (int j = 0; j < 2; ++j) acc[i][j] = MFMA(af[s][i], bfr[s][j], acc[i][j]);
;         __builtin_amdgcn_s_setprio(0);
;       }
;     }
;     ...
;   const int row = tid >> 1, half = tid & 1;
;   float* crow = Cs + row * 132 + half * 64;
;   const float4* crow4 = (const float4*)crow;
;   const int m = tm * RB + hh * 128 + row;
;   const int col0 = tn * 128 + half * 64;
;   if constexpr (MODE == G_INPROJ) {
;     u16* proj = (u16*)(p.ws + OFF_PROJ);
;     const int region = col0 >> 6;
;     const float* g = nullptr; float extra = 1.f;
;     if (region < 8) { g = p.q_g; extra = 0.125f; }
;     else if (region == 12 || region == 13) g = p.ks_g;
;     else if (region == 16 || region == 17) g = p.kw_g;
	ds_read_b128 v[186:189], v176
	ds_read_b128 v[194:197], v176 offset:2560
	ds_read_b128 v[206:209], v176 offset:5120
	ds_read_b128 v[214:217], v179
	ds_read_b128 v[222:225], v178 offset:20480
	ds_read_b128 v[230:233], v178 offset:23040
	v_mfma_f32_32x32x16_f16 v[112:127], v[190:193], v[226:229], v[112:127]
	v_mfma_f32_32x32x16_f16 v[96:111], v[190:193], v[234:237], v[96:111]
	v_mfma_f32_32x32x16_f16 v[80:95], v[198:201], v[226:229], v[80:95]
	v_mfma_f32_32x32x16_f16 v[64:79], v[198:201], v[234:237], v[64:79]
	v_mfma_f32_32x32x16_f16 v[48:63], v[210:213], v[226:229], v[48:63]
	v_mfma_f32_32x32x16_f16 v[32:47], v[210:213], v[234:237], v[32:47]
	v_mfma_f32_32x32x16_f16 v[16:31], v[218:221], v[226:229], v[16:31]
	v_mfma_f32_32x32x16_f16 v[0:15], v[218:221], v[234:237], v[0:15]
	s_setprio 0
	s_cmpk_eq_i32 s6, 0x80
	s_cbranch_scc0 .Lgk_inproj_loop
	ds_read_b128 v[190:193], v176 offset:32
	ds_read_b128 v[198:201], v176 offset:2592
	ds_read_b128 v[210:213], v176 offset:5152
	ds_read_b128 v[218:221], v179 offset:32
	ds_read_b128 v[226:229], v178 offset:20512
	ds_read_b128 v[234:237], v178 offset:23072
	s_setprio 1
	s_waitcnt lgkmcnt(6)
	v_mfma_f32_32x32x16_f16 v[112:127], v[186:189], v[222:225], v[112:127]
	s_waitcnt vmcnt(5)
	ds_write_b128 v181, v[132:135] offset:32768
	v_mfma_f32_32x32x16_f16 v[96:111], v[186:189], v[230:233], v[96:111]
	s_waitcnt vmcnt(4)
	ds_write_b128 v180, v[128:131] offset:32768
	v_mfma_f32_32x32x16_f16 v[80:95], v[194:197], v[222:225], v[80:95]
	s_waitcnt vmcnt(3)
	ds_write_b128 v183, v[140:143] offset:32768
	v_mfma_f32_32x32x16_f16 v[64:79], v[194:197], v[230:233], v[64:79]
	s_waitcnt vmcnt(2)
	ds_write_b128 v182, v[136:139] offset:32768
	v_mfma_f32_32x32x16_f16 v[48:63], v[206:209], v[222:225], v[48:63]
	s_waitcnt vmcnt(1)
	ds_write_b128 v181, v[148:151] offset:53248
	v_mfma_f32_32x32x16_f16 v[32:47], v[206:209], v[230:233], v[32:47]
	s_waitcnt vmcnt(0)
	ds_write_b128 v180, v[144:147] offset:53248
	v_mfma_f32_32x32x16_f16 v[16:31], v[214:217], v[222:225], v[16:31]
	v_mfma_f32_32x32x16_f16 v[0:15], v[214:217], v[230:233], v[0:15]
	s_waitcnt lgkmcnt(0)
	s_barrier
	ds_read_b128 v[186:189], v176 offset:32768
	ds_read_b128 v[194:197], v176 offset:35328
	ds_read_b128 v[206:209], v176 offset:37888
	ds_read_b128 v[214:217], v179 offset:32768
	ds_read_b128 v[222:225], v178 offset:53248
	ds_read_b128 v[230:233], v178 offset:55808
	v_mfma_f32_32x32x16_f16 v[112:127], v[190:193], v[226:229], v[112:127]
	v_mfma_f32_32x32x16_f16 v[96:111], v[190:193], v[234:237], v[96:111]
	v_mfma_f32_32x32x16_f16 v[80:95], v[198:201], v[226:229], v[80:95]
	v_mfma_f32_32x32x16_f16 v[64:79], v[198:201], v[234:237], v[64:79]
	v_mfma_f32_32x32x16_f16 v[48:63], v[210:213], v[226:229], v[48:63]
	v_mfma_f32_32x32x16_f16 v[32:47], v[210:213], v[234:237], v[32:47]
	v_mfma_f32_32x32x16_f16 v[16:31], v[218:221], v[226:229], v[16:31]
	v_mfma_f32_32x32x16_f16 v[0:15], v[218:221], v[234:237], v[0:15]
	s_setprio 0
	ds_read_b128 v[190:193], v176 offset:32800
	ds_read_b128 v[198:201], v176 offset:35360
	ds_read_b128 v[210:213], v176 offset:37920
	ds_read_b128 v[218:221], v179 offset:32800
	ds_read_b128 v[226:229], v178 offset:53280
	ds_read_b128 v[234:237], v178 offset:55840
	s_setprio 1
	s_waitcnt lgkmcnt(6)
	v_mfma_f32_32x32x16_f16 v[112:127], v[186:189], v[222:225], v[112:127]
	v_mfma_f32_32x32x16_f16 v[96:111], v[186:189], v[230:233], v[96:111]
	v_mfma_f32_32x32x16_f16 v[80:95], v[194:197], v[222:225], v[80:95]
	v_mfma_f32_32x32x16_f16 v[64:79], v[194:197], v[230:233], v[64:79]
	v_mfma_f32_32x32x16_f16 v[48:63], v[206:209], v[222:225], v[48:63]
	v_mfma_f32_32x32x16_f16 v[32:47], v[206:209], v[230:233], v[32:47]
	v_mfma_f32_32x32x16_f16 v[16:31], v[214:217], v[222:225], v[16:31]
	v_mfma_f32_32x32x16_f16 v[0:15], v[214:217], v[230:233], v[0:15]
	s_waitcnt lgkmcnt(0)
	v_mfma_f32_32x32x16_f16 v[112:127], v[190:193], v[226:229], v[112:127]
	v_mfma_f32_32x32x16_f16 v[96:111], v[190:193], v[234:237], v[96:111]
	v_mfma_f32_32x32x16_f16 v[80:95], v[198:201], v[226:229], v[80:95]
	v_mfma_f32_32x32x16_f16 v[64:79], v[198:201], v[234:237], v[64:79]
	v_mfma_f32_32x32x16_f16 v[48:63], v[210:213], v[226:229], v[48:63]
	v_mfma_f32_32x32x16_f16 v[32:47], v[210:213], v[234:237], v[32:47]
	v_mfma_f32_32x32x16_f16 v[16:31], v[218:221], v[226:229], v[16:31]
	v_mfma_f32_32x32x16_f16 v[0:15], v[218:221], v[234:237], v[0:15]
	s_setprio 0
	v_ashrrev_i32_e32 v128, 1, v175
	v_lshlrev_b32_e32 v130, 6, v175
	v_mul_lo_u32 v129, v128, s27
	v_and_b32_e32 v130, 64, v130
	v_add_u32_e32 v160, s0, v128
	v_lshlrev_b32_e32 v128, 8, v172
	v_or_b32_e32 v148, s1, v130
	v_lshl_or_b32 v128, v174, 2, v128
	v_ashrrev_i32_e32 v158, 7, v175
	v_lshl_add_u32 v159, v130, 2, v129
	v_cmp_lt_i32_e64 s[6:7], s28, v148
	v_ashrrev_i32_e32 v149, 31, v148
	v_cmp_eq_u32_e64 s[8:9], s29, v148
	v_mad_u32_u24 v161, v167, s30, v128
	s_mov_b32 s38, 0
	s_mov_b64 s[0:1], -1
	s_branch .LBB0_125

; #define MFMA(a, b, c) __builtin_amdgcn_mfma_f32_32x32x16_f16(__builtin_bit_cast(h16x8, (a)), __builtin_bit_cast(h16x8, (b)), (c), 0, 0, 0)
; template <int MODE, bool BIG = false> DI void gemm_tile(const Params& p, int tm, int tn, int kv, char* smem) {
;     ...
;     char* Bs2 = smem + 256 * 80;
;     uint4 ra[4], rb[2];
; #pragma unroll
;     for (int i = 0; i < 4; ++i) { const int id = tid + 256 * i; ra[i] = load_a<MODE>(p, tma, kv, id >> 2, 0, id & 3); }
; #pragma unroll
;     for (int i = 0; i < 2; ++i) { const int id = tid + 256 * i; rb[i] = load_b<MODE>(p, tn, kv, id >> 2, 0, id & 3); }
;     for (int kt = 0; kt < 2 * KT; ++kt) {
;       __syncthreads();
; #pragma unroll
;       for (int i = 0; i < 4; ++i) { const int id = tid + 256 * i; *(uint4*)(As + (id >> 2) * 80 + (id & 3) * 16) = ra[i]; }
; #pragma unroll
;       for (int i = 0; i < 2; ++i) { const int id = tid + 256 * i; *(uint4*)(Bs2 + (id >> 2) * 80 + (id & 3) * 16) = rb[i]; }
;       __syncthreads();
;       if (kt + 1 < 2 * KT) {
;         const int k1 = kt + 1;
; #pragma unroll
;         for (int i = 0; i < 4; ++i) { const int id = tid + 256 * i; ra[i] = load_a<MODE>(p, tma, kv, id >> 2, k1 >> 1, ((k1 & 1) << 2) | (id & 3)); }
; #pragma unroll
;         for (int i = 0; i < 2; ++i) { const int id = tid + 256 * i; rb[i] = load_b<MODE>(p, tn, kv, id >> 2, k1 >> 1, ((k1 & 1) << 2) | (id & 3)); }
;       }
;       {
;         bf16x8 af[2][4], bfr[2][2];
; #pragma unroll
;         for (int s = 0; s < 2; ++s) {
; #pragma unroll
;           for (int i = 0; i < 4; ++i) af[s][i] = *(const bf16x8*)(As + (wm * 128 + i * 32 + r) * 80 + s * 32 + hf * 16);
; #pragma unroll
;           for (int j = 0; j < 2; ++j) bfr[s][j] = *(const bf16x8*)(Bs2 + (wn * 64 + j * 32 + r) * 80 + s * 32 + hf * 16);
;         }
;         __builtin_amdgcn_s_setprio(1);
; #pragma unroll
;         for (int s = 0; s < 2; ++s)
; #pragma unroll
;           for (int i = 0; i < 4; ++i)
; #pragma unroll
;             for (int j = 0; j < 2; ++j) acc[i][j] = MFMA(af[s][i], bfr[s][j], acc[i][j]);
;         __builtin_amdgcn_s_setprio(0);
;       }
;     }
.LBB0_938:
	s_barrier
	s_waitcnt vmcnt(5)
	ds_write_b128 v179, v[132:135]
	s_waitcnt vmcnt(4)
	ds_write_b128 v178, v[128:131]
	s_waitcnt vmcnt(3)
	ds_write_b128 v181, v[140:143]
	s_waitcnt vmcnt(2)
	ds_write_b128 v180, v[136:139]
	s_waitcnt vmcnt(1)
	ds_write_b128 v179, v[148:151] offset:20480
	s_waitcnt vmcnt(0)
	ds_write_b128 v178, v[144:147] offset:20480
	s_and_b32 s14, s7, 0x7c0
	s_lshl_b32 s16, s14, 1
	v_and_or_b32 v128, s6, 4, v182
	s_add_u32 s14, s24, s16
	v_lshlrev_b32_e32 v152, 4, v128
	s_addc_u32 s15, s25, 0
	v_lshl_add_u64 v[128:129], s[14:15], 0, v[152:153]
	s_add_u32 s14, s0, s16
	v_lshl_add_u64 v[130:131], v[128:129], 0, v[154:155]
	v_lshl_add_u64 v[136:137], v[128:129], 0, v[156:157]
	v_lshl_add_u64 v[138:139], v[128:129], 0, v[158:159]
	v_lshl_add_u64 v[144:145], v[128:129], 0, v[160:161]
	s_addc_u32 s15, s1, 0
	global_load_dwordx4 v[132:135], v[130:131], off
	s_nop 0
	global_load_dwordx4 v[128:131], v[136:137], off
	global_load_dwordx4 v[140:143], v[138:139], off
	s_nop 0
	global_load_dwordx4 v[136:139], v[144:145], off
	v_lshl_add_u64 v[144:145], s[14:15], 0, v[152:153]
	v_lshl_add_u64 v[146:147], v[144:145], 0, v[162:163]
	v_lshl_add_u64 v[144:145], v[144:145], 0, v[166:167]
	global_load_dwordx4 v[148:151], v[146:147], off
	s_nop 0
	global_load_dwordx4 v[144:147], v[144:145], off
	s_add_i32 s6, s6, 4
	s_add_i32 s7, s7, 32
	s_waitcnt lgkmcnt(0)
	s_barrier
	ds_read_b128 v[184:187], v174
	ds_read_b128 v[192:195], v174 offset:2560
	ds_read_b128 v[200:203], v174 offset:5120
	ds_read_b128 v[208:211], v176
	ds_read_b128 v[216:219], v175 offset:20480
	ds_read_b128 v[224:227], v175 offset:23040
.Lgk_out_loop:
	ds_read_b128 v[188:191], v174 offset:32
	ds_read_b128 v[196:199], v174 offset:2592
	ds_read_b128 v[204:207], v174 offset:5152
	ds_read_b128 v[212:215], v176 offset:32
	ds_read_b128 v[220:223], v175 offset:20512
	ds_read_b128 v[228:231], v175 offset:23072
	s_setprio 1
	s_waitcnt lgkmcnt(6)
	v_mfma_f32_32x32x16_f16 v[112:127], v[184:187], v[216:219], v[112:127]
	s_waitcnt vmcnt(5)
	ds_write_b128 v179, v[132:135] offset:32768
	v_mfma_f32_32x32x16_f16 v[96:111], v[184:187], v[224:227], v[96:111]
	s_waitcnt vmcnt(4)
	ds_write_b128 v178, v[128:131] offset:32768
	v_mfma_f32_32x32x16_f16 v[80:95], v[192:195], v[216:219], v[80:95]
	s_waitcnt vmcnt(3)
	ds_write_b128 v181, v[140:143] offset:32768
	v_mfma_f32_32x32x16_f16 v[64:79], v[192:195], v[224:227], v[64:79]
	s_waitcnt vmcnt(2)
	ds_write_b128 v180, v[136:139] offset:32768
	v_mfma_f32_32x32x16_f16 v[48:63], v[200:203], v[216:219], v[48:63]
	s_waitcnt vmcnt(1)
	ds_write_b128 v179, v[148:151] offset:53248
	v_mfma_f32_32x32x16_f16 v[32:47], v[200:203], v[224:227], v[32:47]
	s_waitcnt vmcnt(0)
	ds_write_b128 v178, v[144:147] offset:53248
	v_mfma_f32_32x32x16_f16 v[16:31], v[208:211], v[216:219], v[16:31]
	s_and_b32 s14, s7, 0x7c0
	s_lshl_b32 s16, s14, 1
	v_and_or_b32 v128, s6, 4, v182
	s_add_u32 s14, s24, s16
	v_lshlrev_b32_e32 v152, 4, v128
	s_addc_u32 s15, s25, 0
	v_lshl_add_u64 v[128:129], s[14:15], 0, v[152:153]
	s_add_u32 s14, s0, s16
	v_lshl_add_u64 v[130:131], v[128:129], 0, v[154:155]
	v_lshl_add_u64 v[136:137], v[128:129], 0, v[156:157]
	v_mfma_f32_32x32x16_f16 v[0:15], v[208:211], v[224:227], v[0:15]
	v_lshl_add_u64 v[138:139], v[128:129], 0, v[158:159]
	v_lshl_add_u64 v[144:145], v[128:129], 0, v[160:161]
	s_addc_u32 s15, s1, 0
	global_load_dwordx4 v[132:135], v[130:131], off
	s_nop 0
	global_load_dwordx4 v[128:131], v[136:137], off
	global_load_dwordx4 v[140:143], v[138:139], off
	s_nop 0
	global_load_dwordx4 v[136:139], v[144:145], off
	v_lshl_add_u64 v[144:145], s[14:15], 0, v[152:153]
	v_lshl_add_u64 v[146:147], v[144:145], 0, v[162:163]
	v_lshl_add_u64 v[144:145], v[144:145], 0, v[166:167]
	global_load_dwordx4 v[148:151], v[146:147], off
	s_nop 0
	global_load_dwordx4 v[144:147], v[144:145], off
	s_add_i32 s6, s6, 4
	s_add_i32 s7, s7, 32
	s_waitcnt lgkmcnt(0)
	s_barrier
	ds_read_b128 v[184:187], v174 offset:32768
	ds_read_b128 v[192:195], v174 offset:35328
	ds_read_b128 v[200:203], v174 offset:37888
	ds_read_b128 v[208:211], v176 offset:32768
	ds_read_b128 v[216:219], v175 offset:53248
	ds_read_b128 v[224:227], v175 offset:55808
	v_mfma_f32_32x32x16_f16 v[112:127], v[188:191], v[220:223], v[112:127]
	v_mfma_f32_32x32x16_f16 v[96:111], v[188:191], v[228:231], v[96:111]
	v_mfma_f32_32x32x16_f16 v[80:95], v[196:199], v[220:223], v[80:95]
	v_mfma_f32_32x32x16_f16 v[64:79], v[196:199], v[228:231], v[64:79]
	v_mfma_f32_32x32x16_f16 v[48:63], v[204:207], v[220:223], v[48:63]
	v_mfma_f32_32x32x16_f16 v[32:47], v[204:207], v[228:231], v[32:47]
	v_mfma_f32_32x32x16_f16 v[16:31], v[212:215], v[220:223], v[16:31]
	v_mfma_f32_32x32x16_f16 v[0:15], v[212:215], v[228:231], v[0:15]
	s_setprio 0
	ds_read_b128 v[188:191], v174 offset:32800
	ds_read_b128 v[196:199], v174 offset:35360
	ds_read_b128 v[204:207], v174 offset:37920
	ds_read_b128 v[212:215], v176 offset:32800
	ds_read_b128 v[220:223], v175 offset:53280
	ds_read_b128 v[228:231], v175 offset:55840
	s_setprio 1
	s_waitcnt lgkmcnt(6)
	v_mfma_f32_32x32x16_f16 v[112:127], v[184:187], v[216:219], v[112:127]
	s_waitcnt vmcnt(5)
	ds_write_b128 v179, v[132:135]
	v_mfma_f32_32x32x16_f16 v[96:111], v[184:187], v[224:227], v[96:111]
	s_waitcnt vmcnt(4)
	ds_write_b128 v178, v[128:131]
	v_mfma_f32_32x32x16_f16 v[80:95], v[192:195], v[216:219], v[80:95]
	s_waitcnt vmcnt(3)
	ds_write_b128 v181, v[140:143]
	v_mfma_f32_32x32x16_f16 v[64:79], v[192:195], v[224:227], v[64:79]
	s_waitcnt vmcnt(2)
	ds_write_b128 v180, v[136:139]
	v_mfma_f32_32x32x16_f16 v[48:63], v[200:203], v[216:219], v[48:63]
	s_waitcnt vmcnt(1)
	ds_write_b128 v179, v[148:151] offset:20480
	v_mfma_f32_32x32x16_f16 v[32:47], v[200:203], v[224:227], v[32:47]
	s_waitcnt vmcnt(0)
	ds_write_b128 v178, v[144:147] offset:20480
	v_mfma_f32_32x32x16_f16 v[16:31], v[208:211], v[216:219], v[16:31]
	s_and_b32 s14, s7, 0x7c0
	s_lshl_b32 s16, s14, 1
	v_and_or_b32 v128, s6, 4, v182
	s_add_u32 s14, s24, s16
	v_lshlrev_b32_e32 v152, 4, v128
	s_addc_u32 s15, s25, 0
	v_lshl_add_u64 v[128:129], s[14:15], 0, v[152:153]
	s_add_u32 s14, s0, s16
	v_lshl_add_u64 v[130:131], v[128:129], 0, v[154:155]
	v_lshl_add_u64 v[136:137], v[128:129], 0, v[156:157]
	v_mfma_f32_32x32x16_f16 v[0:15], v[208:211], v[224:227], v[0:15]
	v_lshl_add_u64 v[138:139], v[128:129], 0, v[158:159]
	v_lshl_add_u64 v[144:145], v[128:129], 0, v[160:161]
	s_addc_u32 s15, s1, 0
	global_load_dwordx4 v[132:135], v[130:131], off
	s_nop 0
	global_load_dwordx4 v[128:131], v[136:137], off
	global_load_dwordx4 v[140:143], v[138:139], off
	s_nop 0
	global_load_dwordx4 v[136:139], v[144:145], off
	v_lshl_add_u64 v[144:145], s[14:15], 0, v[152:153]
	v_lshl_add_u64 v[146:147], v[144:145], 0, v[162:163]
	v_lshl_add_u64 v[144:145], v[144:145], 0, v[166:167]
	global_load_dwordx4 v[148:151], v[146:147], off
	s_nop 0
	global_load_dwordx4 v[144:147], v[144:145], off
	s_add_i32 s6, s6, 4
	s_add_i32 s7, s7, 32
	s_waitcnt lgkmcnt(0)
	s_barrier
; #define MFMA(a, b, c) __builtin_amdgcn_mfma_f32_32x32x16_f16(__builtin_bit_cast(h16x8, (a)), __builtin_bit_cast(h16x8, (b)), (c), 0, 0, 0)
; template <int MODE, bool BIG = false> DI void gemm_tile(const Params& p, int tm, int tn, int kv, char* smem) {
;     ...
;     for (int kt = 0; kt < 2 * KT; ++kt) {
;       __syncthreads();
; #pragma unroll
;       for (int i = 0; i < 4; ++i) { const int id = tid + 256 * i; *(uint4*)(As + (id >> 2) * 80 + (id & 3) * 16) = ra[i]; }
; #pragma unroll
;       for (int i = 0; i < 2; ++i) { const int id = tid + 256 * i; *(uint4*)(Bs2 + (id >> 2) * 80 + (id & 3) * 16) = rb[i]; }
;       __syncthreads();
;       if (kt + 1 < 2 * KT) {
;         const int k1 = kt + 1;
; #pragma unroll
;         for (int i = 0; i < 4; ++i) { const int id = tid + 256 * i; ra[i] = load_a<MODE>(p, tma, kv, id >> 2, k1 >> 1, ((k1 & 1) << 2) | (id & 3)); }
; #pragma unroll
;         for (int i = 0; i < 2; ++i) { const int id = tid + 256 * i; rb[i] = load_b<MODE>(p, tn, kv, id >> 2, k1 >> 1, ((k1 & 1) << 2) | (id & 3)); }
;       }
;       {
;         bf16x8 af[2][4], bfr[2][2];
; #pragma unroll
;         for (int s = 0; s < 2; ++s) {
; #pragma unroll
;           for (int i = 0; i < 4; ++i) af[s][i] = *(const bf16x8*)(As + (wm * 128 + i * 32 + r) * 80 + s * 32 + hf * 16);
; #pragma unroll
;           for (int j = 0; j < 2; ++j) bfr[s][j] = *(const bf16x8*)(Bs2 + (wn * 64 + j * 32 + r) * 80 + s * 32 + hf * 16);
;         }
;         __builtin_amdgcn_s_setprio(1);
; #pragma unroll
;         for (int s = 0; s < 2; ++s)
; #pragma unroll
;           for (int i = 0; i < 4; ++i)
; #pragma unroll
;             for (int j = 0; j < 2; ++j) acc[i][j] = MFMA(af[s][i], bfr[s][j], acc[i][j]);
;         __builtin_amdgcn_s_setprio(0);
;       }
;     }
;     ...
;   const int row = tid >> 1, half = tid & 1;
;   float* crow = Cs + row * 132 + half * 64;
;   const float4* crow4 = (const float4*)crow;
;   const int m = tm * RB + hh * 128 + row;
;   const int col0 = tn * 128 + half * 64;
	ds_read_b128 v[184:187], v174
	ds_read_b128 v[192:195], v174 offset:2560
	ds_read_b128 v[200:203], v174 offset:5120
	ds_read_b128 v[208:211], v176
	ds_read_b128 v[216:219], v175 offset:20480
	ds_read_b128 v[224:227], v175 offset:23040
	v_mfma_f32_32x32x16_f16 v[112:127], v[188:191], v[220:223], v[112:127]
	v_mfma_f32_32x32x16_f16 v[96:111], v[188:191], v[228:231], v[96:111]
	v_mfma_f32_32x32x16_f16 v[80:95], v[196:199], v[220:223], v[80:95]
	v_mfma_f32_32x32x16_f16 v[64:79], v[196:199], v[228:231], v[64:79]
	v_mfma_f32_32x32x16_f16 v[48:63], v[204:207], v[220:223], v[48:63]
	v_mfma_f32_32x32x16_f16 v[32:47], v[204:207], v[228:231], v[32:47]
	v_mfma_f32_32x32x16_f16 v[16:31], v[212:215], v[220:223], v[16:31]
	v_mfma_f32_32x32x16_f16 v[0:15], v[212:215], v[228:231], v[0:15]
	s_setprio 0
	s_cmpk_eq_i32 s6, 0x80
	s_cbranch_scc0 .Lgk_out_loop
	ds_read_b128 v[188:191], v174 offset:32
	ds_read_b128 v[196:199], v174 offset:2592
	ds_read_b128 v[204:207], v174 offset:5152
	ds_read_b128 v[212:215], v176 offset:32
	ds_read_b128 v[220:223], v175 offset:20512
	ds_read_b128 v[228:231], v175 offset:23072
	s_setprio 1
	s_waitcnt lgkmcnt(6)
	v_mfma_f32_32x32x16_f16 v[112:127], v[184:187], v[216:219], v[112:127]
	s_waitcnt vmcnt(5)
	ds_write_b128 v179, v[132:135] offset:32768
	v_mfma_f32_32x32x16_f16 v[96:111], v[184:187], v[224:227], v[96:111]
	s_waitcnt vmcnt(4)
	ds_write_b128 v178, v[128:131] offset:32768
	v_mfma_f32_32x32x16_f16 v[80:95], v[192:195], v[216:219], v[80:95]
	s_waitcnt vmcnt(3)
	ds_write_b128 v181, v[140:143] offset:32768
	v_mfma_f32_32x32x16_f16 v[64:79], v[192:195], v[224:227], v[64:79]
	s_waitcnt vmcnt(2)
	ds_write_b128 v180, v[136:139] offset:32768
	v_mfma_f32_32x32x16_f16 v[48:63], v[200:203], v[216:219], v[48:63]
	s_waitcnt vmcnt(1)
	ds_write_b128 v179, v[148:151] offset:53248
	v_mfma_f32_32x32x16_f16 v[32:47], v[200:203], v[224:227], v[32:47]
	s_waitcnt vmcnt(0)
	ds_write_b128 v178, v[144:147] offset:53248
	v_mfma_f32_32x32x16_f16 v[16:31], v[208:211], v[216:219], v[16:31]
	v_mfma_f32_32x32x16_f16 v[0:15], v[208:211], v[224:227], v[0:15]
	s_waitcnt lgkmcnt(0)
	s_barrier
	ds_read_b128 v[184:187], v174 offset:32768
	ds_read_b128 v[192:195], v174 offset:35328
	ds_read_b128 v[200:203], v174 offset:37888
	ds_read_b128 v[208:211], v176 offset:32768
	ds_read_b128 v[216:219], v175 offset:53248
	ds_read_b128 v[224:227], v175 offset:55808
	v_mfma_f32_32x32x16_f16 v[112:127], v[188:191], v[220:223], v[112:127]
	v_mfma_f32_32x32x16_f16 v[96:111], v[188:191], v[228:231], v[96:111]
	v_mfma_f32_32x32x16_f16 v[80:95], v[196:199], v[220:223], v[80:95]
	v_mfma_f32_32x32x16_f16 v[64:79], v[196:199], v[228:231], v[64:79]
	v_mfma_f32_32x32x16_f16 v[48:63], v[204:207], v[220:223], v[48:63]
	v_mfma_f32_32x32x16_f16 v[32:47], v[204:207], v[228:231], v[32:47]
	v_mfma_f32_32x32x16_f16 v[16:31], v[212:215], v[220:223], v[16:31]
	v_mfma_f32_32x32x16_f16 v[0:15], v[212:215], v[228:231], v[0:15]
	s_setprio 0
	ds_read_b128 v[188:191], v174 offset:32800
	ds_read_b128 v[196:199], v174 offset:35360
	ds_read_b128 v[204:207], v174 offset:37920
	ds_read_b128 v[212:215], v176 offset:32800
	ds_read_b128 v[220:223], v175 offset:53280
	ds_read_b128 v[228:231], v175 offset:55840
	s_setprio 1
	s_waitcnt lgkmcnt(6)
	v_mfma_f32_32x32x16_f16 v[112:127], v[184:187], v[216:219], v[112:127]
	v_mfma_f32_32x32x16_f16 v[96:111], v[184:187], v[224:227], v[96:111]
	v_mfma_f32_32x32x16_f16 v[80:95], v[192:195], v[216:219], v[80:95]
	v_mfma_f32_32x32x16_f16 v[64:79], v[192:195], v[224:227], v[64:79]
	v_mfma_f32_32x32x16_f16 v[48:63], v[200:203], v[216:219], v[48:63]
	v_mfma_f32_32x32x16_f16 v[32:47], v[200:203], v[224:227], v[32:47]
	v_mfma_f32_32x32x16_f16 v[16:31], v[208:211], v[216:219], v[16:31]
	v_mfma_f32_32x32x16_f16 v[0:15], v[208:211], v[224:227], v[0:15]
	s_waitcnt lgkmcnt(0)
	v_mfma_f32_32x32x16_f16 v[112:127], v[188:191], v[220:223], v[112:127]
	v_mfma_f32_32x32x16_f16 v[96:111], v[188:191], v[228:231], v[96:111]
	v_mfma_f32_32x32x16_f16 v[80:95], v[196:199], v[220:223], v[80:95]
	v_mfma_f32_32x32x16_f16 v[64:79], v[196:199], v[228:231], v[64:79]
	v_mfma_f32_32x32x16_f16 v[48:63], v[204:207], v[220:223], v[48:63]
	v_mfma_f32_32x32x16_f16 v[32:47], v[204:207], v[228:231], v[32:47]
	v_mfma_f32_32x32x16_f16 v[16:31], v[212:215], v[220:223], v[16:31]
	v_mfma_f32_32x32x16_f16 v[0:15], v[212:215], v[228:231], v[0:15]
	s_setprio 0
	v_ashrrev_i32_e32 v128, 1, v172
	v_lshlrev_b32_e32 v130, 6, v172
	v_mul_lo_u32 v129, v128, s9
	v_and_b32_e32 v130, 64, v130
	v_lshl_add_u32 v133, v130, 2, v129
	v_add_u32_e32 v134, s2, v128
	v_or_b32_e32 v128, s3, v130
	v_lshlrev_b32_e32 v129, 8, v170
	v_readlane_b32 s16, v252, 2
	v_lshl_or_b32 v129, v171, 2, v129
	v_lshlrev_b32_e32 v152, 2, v128
	v_readlane_b32 s18, v252, 4
	v_readlane_b32 s19, v252, 5
	v_ashrrev_i32_e32 v132, 7, v172
	v_mad_u32_u24 v135, v165, s10, v129
	v_lshl_add_u64 v[128:129], s[36:37], 0, v[152:153]
	v_lshl_add_u64 v[130:131], s[18:19], 0, v[152:153]
	s_mov_b32 s14, 0
	s_mov_b64 s[2:3], -1
	v_readlane_b32 s17, v252, 3
	s_branch .LBB0_941

; #define MFMA(a, b, c) __builtin_amdgcn_mfma_f32_32x32x16_f16(__builtin_bit_cast(h16x8, (a)), __builtin_bit_cast(h16x8, (b)), (c), 0, 0, 0)
; DI size_t hid_off(int m, int c) { const int ml = m & 4095; return (size_t)(m >> 12) * (SLAB / 2) + ((size_t)((ml >> 8) * 128 + (c >> 5)) << 13) + (size_t)((ml & 255) * 32 + (c & 31)); }
; template <int MODE, bool BIG = false> DI void gemm_tile(const Params& p, int tm, int tn, int kv, char* smem) {
;     ...
;     char* Bs2 = smem + 256 * 80;
;     uint4 ra[4], rb[2];
; #pragma unroll
;     for (int i = 0; i < 4; ++i) { const int id = tid + 256 * i; ra[i] = load_a<MODE>(p, tma, kv, id >> 2, 0, id & 3); }
; #pragma unroll
;     for (int i = 0; i < 2; ++i) { const int id = tid + 256 * i; rb[i] = load_b<MODE>(p, tn, kv, id >> 2, 0, id & 3); }
;     for (int kt = 0; kt < 2 * KT; ++kt) {
;       __syncthreads();
; #pragma unroll
;       for (int i = 0; i < 4; ++i) { const int id = tid + 256 * i; *(uint4*)(As + (id >> 2) * 80 + (id & 3) * 16) = ra[i]; }
; #pragma unroll
;       for (int i = 0; i < 2; ++i) { const int id = tid + 256 * i; *(uint4*)(Bs2 + (id >> 2) * 80 + (id & 3) * 16) = rb[i]; }
;       __syncthreads();
;       if (kt + 1 < 2 * KT) {
;         const int k1 = kt + 1;
; #pragma unroll
;         for (int i = 0; i < 4; ++i) { const int id = tid + 256 * i; ra[i] = load_a<MODE>(p, tma, kv, id >> 2, k1 >> 1, ((k1 & 1) << 2) | (id & 3)); }
; #pragma unroll
;         for (int i = 0; i < 2; ++i) { const int id = tid + 256 * i; rb[i] = load_b<MODE>(p, tn, kv, id >> 2, k1 >> 1, ((k1 & 1) << 2) | (id & 3)); }
;       }
;       {
;         bf16x8 af[2][4], bfr[2][2];
; #pragma unroll
;         for (int s = 0; s < 2; ++s) {
; #pragma unroll
;           for (int i = 0; i < 4; ++i) af[s][i] = *(const bf16x8*)(As + (wm * 128 + i * 32 + r) * 80 + s * 32 + hf * 16);
; #pragma unroll
;           for (int j = 0; j < 2; ++j) bfr[s][j] = *(const bf16x8*)(Bs2 + (wn * 64 + j * 32 + r) * 80 + s * 32 + hf * 16);
;         }
;         __builtin_amdgcn_s_setprio(1);
; #pragma unroll
;         for (int s = 0; s < 2; ++s)
; #pragma unroll
;           for (int i = 0; i < 4; ++i)
; #pragma unroll
;             for (int j = 0; j < 2; ++j) acc[i][j] = MFMA(af[s][i], bfr[s][j], acc[i][j]);
;         __builtin_amdgcn_s_setprio(0);
;       }
;     }
.LBB0_1001:
	s_barrier
	s_waitcnt vmcnt(5)
	ds_write_b128 v179, v[132:135]
	s_waitcnt vmcnt(4)
	ds_write_b128 v178, v[128:131]
	s_waitcnt vmcnt(3)
	ds_write_b128 v182, v[140:143]
	s_waitcnt vmcnt(2)
	ds_write_b128 v181, v[136:139]
	s_waitcnt vmcnt(1)
	ds_write_b128 v179, v[148:151] offset:20480
	s_waitcnt vmcnt(0)
	ds_write_b128 v178, v[144:147] offset:20480
	v_and_or_b32 v138, s6, 4, v180
	s_and_b32 s14, s7, 0x1fc0
	v_lshlrev_b32_e32 v128, 3, v138
	v_or_b32_e32 v129, s14, v128
	v_and_b32_e32 v128, 24, v128
	v_lshrrev_b32_e32 v139, 5, v129
	v_or_b32_e32 v130, v128, v170
	v_add_lshl_u32 v152, v139, v183, 14
	v_or_b32_e32 v131, v128, v171
	v_or_b32_e32 v140, v128, v172
	v_or_b32_e32 v144, v128, v174
	v_lshl_add_u64 v[128:129], v[158:159], 0, v[152:153]
	v_lshlrev_b32_e32 v152, 1, v130
	v_lshl_add_u64 v[128:129], v[128:129], 0, v[152:153]
	v_add_lshl_u32 v152, v139, v184, 14
	global_load_dwordx4 v[132:135], v[128:129], off
	v_lshl_add_u64 v[128:129], v[160:161], 0, v[152:153]
	v_lshlrev_b32_e32 v152, 1, v131
	v_lshl_add_u64 v[128:129], v[128:129], 0, v[152:153]
	v_add_lshl_u32 v152, v139, v185, 14
	v_lshl_add_u64 v[136:137], v[162:163], 0, v[152:153]
	v_lshlrev_b32_e32 v152, 1, v140
	s_lshl_b32 s15, s14, 1
	v_lshl_add_u64 v[136:137], v[136:137], 0, v[152:153]
	v_add_lshl_u32 v152, v139, v186, 14
	s_add_u32 s14, s2, s15
	global_load_dwordx4 v[128:131], v[128:129], off
	s_addc_u32 s15, s3, 0
	global_load_dwordx4 v[140:143], v[136:137], off
	v_lshl_add_u64 v[136:137], v[164:165], 0, v[152:153]
	v_lshlrev_b32_e32 v152, 1, v144
	v_lshl_add_u64 v[136:137], v[136:137], 0, v[152:153]
	v_lshlrev_b32_e32 v152, 4, v138
	v_lshl_add_u64 v[144:145], s[14:15], 0, v[152:153]
	v_lshl_add_u64 v[146:147], v[144:145], 0, v[154:155]
	v_lshl_add_u64 v[144:145], v[144:145], 0, v[156:157]
	global_load_dwordx4 v[136:139], v[136:137], off
	s_nop 0
	global_load_dwordx4 v[148:151], v[146:147], off
	s_nop 0
	global_load_dwordx4 v[144:147], v[144:145], off
	s_add_i32 s6, s6, 4
	s_add_i32 s7, s7, 32
	s_waitcnt lgkmcnt(0)
	s_barrier
	ds_read_b128 v[188:191], v175
	ds_read_b128 v[196:199], v175 offset:2560
	ds_read_b128 v[204:207], v175 offset:5120
	ds_read_b128 v[212:215], v177
	ds_read_b128 v[220:223], v176 offset:20480
	ds_read_b128 v[228:231], v176 offset:23040
.Lgk_ff2_loop:
	ds_read_b128 v[192:195], v175 offset:32
	ds_read_b128 v[200:203], v175 offset:2592
	ds_read_b128 v[208:211], v175 offset:5152
	ds_read_b128 v[216:219], v177 offset:32
	ds_read_b128 v[224:227], v176 offset:20512
	ds_read_b128 v[232:235], v176 offset:23072
	s_setprio 1
	s_waitcnt lgkmcnt(6)
	v_mfma_f32_32x32x16_f16 v[112:127], v[188:191], v[220:223], v[112:127]
	s_waitcnt vmcnt(5)
	ds_write_b128 v179, v[132:135] offset:32768
	v_mfma_f32_32x32x16_f16 v[96:111], v[188:191], v[228:231], v[96:111]
	s_waitcnt vmcnt(4)
	ds_write_b128 v178, v[128:131] offset:32768
	v_mfma_f32_32x32x16_f16 v[80:95], v[196:199], v[220:223], v[80:95]
	s_waitcnt vmcnt(3)
	ds_write_b128 v182, v[140:143] offset:32768
	v_mfma_f32_32x32x16_f16 v[64:79], v[196:199], v[228:231], v[64:79]
	s_waitcnt vmcnt(2)
	ds_write_b128 v181, v[136:139] offset:32768
	v_mfma_f32_32x32x16_f16 v[48:63], v[204:207], v[220:223], v[48:63]
	s_waitcnt vmcnt(1)
	ds_write_b128 v179, v[148:151] offset:53248
	v_mfma_f32_32x32x16_f16 v[32:47], v[204:207], v[228:231], v[32:47]
	s_waitcnt vmcnt(0)
	ds_write_b128 v178, v[144:147] offset:53248
	v_mfma_f32_32x32x16_f16 v[16:31], v[212:215], v[220:223], v[16:31]
	v_and_or_b32 v138, s6, 4, v180
	s_and_b32 s14, s7, 0x1fc0
	v_lshlrev_b32_e32 v128, 3, v138
	v_or_b32_e32 v129, s14, v128
	v_and_b32_e32 v128, 24, v128
	v_lshrrev_b32_e32 v139, 5, v129
	v_or_b32_e32 v130, v128, v170
	v_add_lshl_u32 v152, v139, v183, 14
	v_or_b32_e32 v131, v128, v171
	v_or_b32_e32 v140, v128, v172
	v_or_b32_e32 v144, v128, v174
	v_lshl_add_u64 v[128:129], v[158:159], 0, v[152:153]
	v_lshlrev_b32_e32 v152, 1, v130
	v_lshl_add_u64 v[128:129], v[128:129], 0, v[152:153]
	v_add_lshl_u32 v152, v139, v184, 14
	global_load_dwordx4 v[132:135], v[128:129], off
	v_mfma_f32_32x32x16_f16 v[0:15], v[212:215], v[228:231], v[0:15]
	v_lshl_add_u64 v[128:129], v[160:161], 0, v[152:153]
	v_lshlrev_b32_e32 v152, 1, v131
	v_lshl_add_u64 v[128:129], v[128:129], 0, v[152:153]
	v_add_lshl_u32 v152, v139, v185, 14
	v_lshl_add_u64 v[136:137], v[162:163], 0, v[152:153]
	v_lshlrev_b32_e32 v152, 1, v140
	s_lshl_b32 s15, s14, 1
	v_lshl_add_u64 v[136:137], v[136:137], 0, v[152:153]
	v_add_lshl_u32 v152, v139, v186, 14
	s_add_u32 s14, s2, s15
	global_load_dwordx4 v[128:131], v[128:129], off
	s_addc_u32 s15, s3, 0
	global_load_dwordx4 v[140:143], v[136:137], off
	v_lshl_add_u64 v[136:137], v[164:165], 0, v[152:153]
	v_lshlrev_b32_e32 v152, 1, v144
	v_lshl_add_u64 v[136:137], v[136:137], 0, v[152:153]
	v_lshlrev_b32_e32 v152, 4, v138
	v_lshl_add_u64 v[144:145], s[14:15], 0, v[152:153]
	v_lshl_add_u64 v[146:147], v[144:145], 0, v[154:155]
	v_lshl_add_u64 v[144:145], v[144:145], 0, v[156:157]
	global_load_dwordx4 v[136:139], v[136:137], off
	s_nop 0
	global_load_dwordx4 v[148:151], v[146:147], off
	s_nop 0
	global_load_dwordx4 v[144:147], v[144:145], off
	s_add_i32 s6, s6, 4
	s_add_i32 s7, s7, 32
	s_waitcnt lgkmcnt(0)
	s_barrier
; #define MFMA(a, b, c) __builtin_amdgcn_mfma_f32_32x32x16_f16(__builtin_bit_cast(h16x8, (a)), __builtin_bit_cast(h16x8, (b)), (c), 0, 0, 0)
; template <int MODE, bool BIG = false> DI void gemm_tile(const Params& p, int tm, int tn, int kv, char* smem) {
;     ...
;     char* Bs2 = smem + 256 * 80;
;     uint4 ra[4], rb[2];
; #pragma unroll
;     for (int i = 0; i < 4; ++i) { const int id = tid + 256 * i; ra[i] = load_a<MODE>(p, tma, kv, id >> 2, 0, id & 3); }
; #pragma unroll
;     for (int i = 0; i < 2; ++i) { const int id = tid + 256 * i; rb[i] = load_b<MODE>(p, tn, kv, id >> 2, 0, id & 3); }
;     for (int kt = 0; kt < 2 * KT; ++kt) {
;       __syncthreads();
; #pragma unroll
;       for (int i = 0; i < 4; ++i) { const int id = tid + 256 * i; *(uint4*)(As + (id >> 2) * 80 + (id & 3) * 16) = ra[i]; }
; #pragma unroll
;       for (int i = 0; i < 2; ++i) { const int id = tid + 256 * i; *(uint4*)(Bs2 + (id >> 2) * 80 + (id & 3) * 16) = rb[i]; }
;       __syncthreads();
;       if (kt + 1 < 2 * KT) {
;         const int k1 = kt + 1;
; #pragma unroll
;         for (int i = 0; i < 4; ++i) { const int id = tid + 256 * i; ra[i] = load_a<MODE>(p, tma, kv, id >> 2, k1 >> 1, ((k1 & 1) << 2) | (id & 3)); }
; #pragma unroll
;         for (int i = 0; i < 2; ++i) { const int id = tid + 256 * i; rb[i] = load_b<MODE>(p, tn, kv, id >> 2, k1 >> 1, ((k1 & 1) << 2) | (id & 3)); }
;       }
;       {
;         bf16x8 af[2][4], bfr[2][2];
; #pragma unroll
;         for (int s = 0; s < 2; ++s) {
; #pragma unroll
;           for (int i = 0; i < 4; ++i) af[s][i] = *(const bf16x8*)(As + (wm * 128 + i * 32 + r) * 80 + s * 32 + hf * 16);
; #pragma unroll
;           for (int j = 0; j < 2; ++j) bfr[s][j] = *(const bf16x8*)(Bs2 + (wn * 64 + j * 32 + r) * 80 + s * 32 + hf * 16);
;         }
;         __builtin_amdgcn_s_setprio(1);
; #pragma unroll
;         for (int s = 0; s < 2; ++s)
; #pragma unroll
;           for (int i = 0; i < 4; ++i)
; #pragma unroll
;             for (int j = 0; j < 2; ++j) acc[i][j] = MFMA(af[s][i], bfr[s][j], acc[i][j]);
;         __builtin_amdgcn_s_setprio(0);
;       }
;     }
	ds_read_b128 v[188:191], v175 offset:32768
	ds_read_b128 v[196:199], v175 offset:35328
	ds_read_b128 v[204:207], v175 offset:37888
	ds_read_b128 v[212:215], v177 offset:32768
	ds_read_b128 v[220:223], v176 offset:53248
	ds_read_b128 v[228:231], v176 offset:55808
	v_mfma_f32_32x32x16_f16 v[112:127], v[192:195], v[224:227], v[112:127]
	v_mfma_f32_32x32x16_f16 v[96:111], v[192:195], v[232:235], v[96:111]
	v_mfma_f32_32x32x16_f16 v[80:95], v[200:203], v[224:227], v[80:95]
	v_mfma_f32_32x32x16_f16 v[64:79], v[200:203], v[232:235], v[64:79]
	v_mfma_f32_32x32x16_f16 v[48:63], v[208:211], v[224:227], v[48:63]
	v_mfma_f32_32x32x16_f16 v[32:47], v[208:211], v[232:235], v[32:47]
	v_mfma_f32_32x32x16_f16 v[16:31], v[216:219], v[224:227], v[16:31]
	v_mfma_f32_32x32x16_f16 v[0:15], v[216:219], v[232:235], v[0:15]
	s_setprio 0
	ds_read_b128 v[192:195], v175 offset:32800
	ds_read_b128 v[200:203], v175 offset:35360
	ds_read_b128 v[208:211], v175 offset:37920
	ds_read_b128 v[216:219], v177 offset:32800
	ds_read_b128 v[224:227], v176 offset:53280
	ds_read_b128 v[232:235], v176 offset:55840
	s_setprio 1
	s_waitcnt lgkmcnt(6)
	v_mfma_f32_32x32x16_f16 v[112:127], v[188:191], v[220:223], v[112:127]
	s_waitcnt vmcnt(5)
	ds_write_b128 v179, v[132:135]
	v_mfma_f32_32x32x16_f16 v[96:111], v[188:191], v[228:231], v[96:111]
	s_waitcnt vmcnt(4)
	ds_write_b128 v178, v[128:131]
	v_mfma_f32_32x32x16_f16 v[80:95], v[196:199], v[220:223], v[80:95]
	s_waitcnt vmcnt(3)
	ds_write_b128 v182, v[140:143]
	v_mfma_f32_32x32x16_f16 v[64:79], v[196:199], v[228:231], v[64:79]
	s_waitcnt vmcnt(2)
	ds_write_b128 v181, v[136:139]
	v_mfma_f32_32x32x16_f16 v[48:63], v[204:207], v[220:223], v[48:63]
	s_waitcnt vmcnt(1)
	ds_write_b128 v179, v[148:151] offset:20480
	v_mfma_f32_32x32x16_f16 v[32:47], v[204:207], v[228:231], v[32:47]
	s_waitcnt vmcnt(0)
	ds_write_b128 v178, v[144:147] offset:20480
	v_mfma_f32_32x32x16_f16 v[16:31], v[212:215], v[220:223], v[16:31]
	v_and_or_b32 v138, s6, 4, v180
	s_and_b32 s14, s7, 0x1fc0
	v_lshlrev_b32_e32 v128, 3, v138
	v_or_b32_e32 v129, s14, v128
	v_and_b32_e32 v128, 24, v128
	v_lshrrev_b32_e32 v139, 5, v129
	v_or_b32_e32 v130, v128, v170
	v_add_lshl_u32 v152, v139, v183, 14
	v_or_b32_e32 v131, v128, v171
	v_or_b32_e32 v140, v128, v172
	v_or_b32_e32 v144, v128, v174
	v_lshl_add_u64 v[128:129], v[158:159], 0, v[152:153]
	v_lshlrev_b32_e32 v152, 1, v130
	v_lshl_add_u64 v[128:129], v[128:129], 0, v[152:153]
	v_add_lshl_u32 v152, v139, v184, 14
	global_load_dwordx4 v[132:135], v[128:129], off
	v_mfma_f32_32x32x16_f16 v[0:15], v[212:215], v[228:231], v[0:15]
	v_lshl_add_u64 v[128:129], v[160:161], 0, v[152:153]
	v_lshlrev_b32_e32 v152, 1, v131
	v_lshl_add_u64 v[128:129], v[128:129], 0, v[152:153]
	v_add_lshl_u32 v152, v139, v185, 14
	v_lshl_add_u64 v[136:137], v[162:163], 0, v[152:153]
	v_lshlrev_b32_e32 v152, 1, v140
	s_lshl_b32 s15, s14, 1
	v_lshl_add_u64 v[136:137], v[136:137], 0, v[152:153]
	v_add_lshl_u32 v152, v139, v186, 14
	s_add_u32 s14, s2, s15
	global_load_dwordx4 v[128:131], v[128:129], off
	s_addc_u32 s15, s3, 0
	global_load_dwordx4 v[140:143], v[136:137], off
	v_lshl_add_u64 v[136:137], v[164:165], 0, v[152:153]
	v_lshlrev_b32_e32 v152, 1, v144
	v_lshl_add_u64 v[136:137], v[136:137], 0, v[152:153]
	v_lshlrev_b32_e32 v152, 4, v138
	v_lshl_add_u64 v[144:145], s[14:15], 0, v[152:153]
	v_lshl_add_u64 v[146:147], v[144:145], 0, v[154:155]
	v_lshl_add_u64 v[144:145], v[144:145], 0, v[156:157]
	global_load_dwordx4 v[136:139], v[136:137], off
	s_nop 0
	global_load_dwordx4 v[148:151], v[146:147], off
	s_nop 0
	global_load_dwordx4 v[144:147], v[144:145], off
	s_add_i32 s6, s6, 4
	s_add_i32 s7, s7, 32
	s_waitcnt lgkmcnt(0)
	s_barrier
	ds_read_b128 v[188:191], v175
	ds_read_b128 v[196:199], v175 offset:2560
	ds_read_b128 v[204:207], v175 offset:5120
	ds_read_b128 v[212:215], v177
	ds_read_b128 v[220:223], v176 offset:20480
	ds_read_b128 v[228:231], v176 offset:23040
	v_mfma_f32_32x32x16_f16 v[112:127], v[192:195], v[224:227], v[112:127]
	v_mfma_f32_32x32x16_f16 v[96:111], v[192:195], v[232:235], v[96:111]
	v_mfma_f32_32x32x16_f16 v[80:95], v[200:203], v[224:227], v[80:95]
	v_mfma_f32_32x32x16_f16 v[64:79], v[200:203], v[232:235], v[64:79]
	v_mfma_f32_32x32x16_f16 v[48:63], v[208:211], v[224:227], v[48:63]
	v_mfma_f32_32x32x16_f16 v[32:47], v[208:211], v[232:235], v[32:47]
	v_mfma_f32_32x32x16_f16 v[16:31], v[216:219], v[224:227], v[16:31]
	v_mfma_f32_32x32x16_f16 v[0:15], v[216:219], v[232:235], v[0:15]
	s_setprio 0
	s_cmpk_eq_i32 s6, 0x200
	s_cbranch_scc0 .Lgk_ff2_loop
; #define MFMA(a, b, c) __builtin_amdgcn_mfma_f32_32x32x16_f16(__builtin_bit_cast(h16x8, (a)), __builtin_bit_cast(h16x8, (b)), (c), 0, 0, 0)
; template <int MODE, bool BIG = false> DI void gemm_tile(const Params& p, int tm, int tn, int kv, char* smem) {
;     ...
;     for (int kt = 0; kt < 2 * KT; ++kt) {
;       __syncthreads();
; #pragma unroll
;       for (int i = 0; i < 4; ++i) { const int id = tid + 256 * i; *(uint4*)(As + (id >> 2) * 80 + (id & 3) * 16) = ra[i]; }
; #pragma unroll
;       for (int i = 0; i < 2; ++i) { const int id = tid + 256 * i; *(uint4*)(Bs2 + (id >> 2) * 80 + (id & 3) * 16) = rb[i]; }
;       __syncthreads();
;       if (kt + 1 < 2 * KT) {
;         const int k1 = kt + 1;
; #pragma unroll
;         for (int i = 0; i < 4; ++i) { const int id = tid + 256 * i; ra[i] = load_a<MODE>(p, tma, kv, id >> 2, k1 >> 1, ((k1 & 1) << 2) | (id & 3)); }
; #pragma unroll
;         for (int i = 0; i < 2; ++i) { const int id = tid + 256 * i; rb[i] = load_b<MODE>(p, tn, kv, id >> 2, k1 >> 1, ((k1 & 1) << 2) | (id & 3)); }
;       }
;       {
;         bf16x8 af[2][4], bfr[2][2];
; #pragma unroll
;         for (int s = 0; s < 2; ++s) {
; #pragma unroll
;           for (int i = 0; i < 4; ++i) af[s][i] = *(const bf16x8*)(As + (wm * 128 + i * 32 + r) * 80 + s * 32 + hf * 16);
; #pragma unroll
;           for (int j = 0; j < 2; ++j) bfr[s][j] = *(const bf16x8*)(Bs2 + (wn * 64 + j * 32 + r) * 80 + s * 32 + hf * 16);
;         }
;         __builtin_amdgcn_s_setprio(1);
; #pragma unroll
;         for (int s = 0; s < 2; ++s)
; #pragma unroll
;           for (int i = 0; i < 4; ++i)
; #pragma unroll
;             for (int j = 0; j < 2; ++j) acc[i][j] = MFMA(af[s][i], bfr[s][j], acc[i][j]);
;         __builtin_amdgcn_s_setprio(0);
;       }
;     }
;     ...
;   } else if constexpr (MODE == G_FF2) {
;     float4* o4 = (float4*)(p.out + (size_t)m * 1024 + col0);
; #pragma unroll
;     for (int c4 = 0; c4 < 16; ++c4) { float4 v = crow4[c4], xx = o4[c4]; o4[c4] = make_float4(v.x + xx.x, v.y + xx.y, v.z + xx.z, v.w + xx.w); }
	ds_read_b128 v[192:195], v175 offset:32
	ds_read_b128 v[200:203], v175 offset:2592
	ds_read_b128 v[208:211], v175 offset:5152
	ds_read_b128 v[216:219], v177 offset:32
	ds_read_b128 v[224:227], v176 offset:20512
	ds_read_b128 v[232:235], v176 offset:23072
	s_setprio 1
	s_waitcnt lgkmcnt(6)
	v_mfma_f32_32x32x16_f16 v[112:127], v[188:191], v[220:223], v[112:127]
	s_waitcnt vmcnt(5)
	ds_write_b128 v179, v[132:135] offset:32768
	v_mfma_f32_32x32x16_f16 v[96:111], v[188:191], v[228:231], v[96:111]
	s_waitcnt vmcnt(4)
	ds_write_b128 v178, v[128:131] offset:32768
	v_mfma_f32_32x32x16_f16 v[80:95], v[196:199], v[220:223], v[80:95]
	s_waitcnt vmcnt(3)
	ds_write_b128 v182, v[140:143] offset:32768
	v_mfma_f32_32x32x16_f16 v[64:79], v[196:199], v[228:231], v[64:79]
	s_waitcnt vmcnt(2)
	ds_write_b128 v181, v[136:139] offset:32768
	v_mfma_f32_32x32x16_f16 v[48:63], v[204:207], v[220:223], v[48:63]
	s_waitcnt vmcnt(1)
	ds_write_b128 v179, v[148:151] offset:53248
	v_mfma_f32_32x32x16_f16 v[32:47], v[204:207], v[228:231], v[32:47]
	s_waitcnt vmcnt(0)
	ds_write_b128 v178, v[144:147] offset:53248
	v_mfma_f32_32x32x16_f16 v[16:31], v[212:215], v[220:223], v[16:31]
	v_mfma_f32_32x32x16_f16 v[0:15], v[212:215], v[228:231], v[0:15]
	s_waitcnt lgkmcnt(0)
	s_barrier
	ds_read_b128 v[188:191], v175 offset:32768
	ds_read_b128 v[196:199], v175 offset:35328
	ds_read_b128 v[204:207], v175 offset:37888
	ds_read_b128 v[212:215], v177 offset:32768
	ds_read_b128 v[220:223], v176 offset:53248
	ds_read_b128 v[228:231], v176 offset:55808
	v_mfma_f32_32x32x16_f16 v[112:127], v[192:195], v[224:227], v[112:127]
	v_mfma_f32_32x32x16_f16 v[96:111], v[192:195], v[232:235], v[96:111]
	v_mfma_f32_32x32x16_f16 v[80:95], v[200:203], v[224:227], v[80:95]
	v_mfma_f32_32x32x16_f16 v[64:79], v[200:203], v[232:235], v[64:79]
	v_mfma_f32_32x32x16_f16 v[48:63], v[208:211], v[224:227], v[48:63]
	v_mfma_f32_32x32x16_f16 v[32:47], v[208:211], v[232:235], v[32:47]
	v_mfma_f32_32x32x16_f16 v[16:31], v[216:219], v[224:227], v[16:31]
	v_mfma_f32_32x32x16_f16 v[0:15], v[216:219], v[232:235], v[0:15]
	s_setprio 0
	ds_read_b128 v[192:195], v175 offset:32800
	ds_read_b128 v[200:203], v175 offset:35360
	ds_read_b128 v[208:211], v175 offset:37920
	ds_read_b128 v[216:219], v177 offset:32800
	ds_read_b128 v[224:227], v176 offset:53280
	ds_read_b128 v[232:235], v176 offset:55840
	s_setprio 1
	s_waitcnt lgkmcnt(6)
	v_mfma_f32_32x32x16_f16 v[112:127], v[188:191], v[220:223], v[112:127]
	v_mfma_f32_32x32x16_f16 v[96:111], v[188:191], v[228:231], v[96:111]
	v_mfma_f32_32x32x16_f16 v[80:95], v[196:199], v[220:223], v[80:95]
	v_mfma_f32_32x32x16_f16 v[64:79], v[196:199], v[228:231], v[64:79]
	v_mfma_f32_32x32x16_f16 v[48:63], v[204:207], v[220:223], v[48:63]
	v_mfma_f32_32x32x16_f16 v[32:47], v[204:207], v[228:231], v[32:47]
	v_mfma_f32_32x32x16_f16 v[16:31], v[212:215], v[220:223], v[16:31]
	v_mfma_f32_32x32x16_f16 v[0:15], v[212:215], v[228:231], v[0:15]
	s_waitcnt lgkmcnt(0)
	v_mfma_f32_32x32x16_f16 v[112:127], v[192:195], v[224:227], v[112:127]
	v_mfma_f32_32x32x16_f16 v[96:111], v[192:195], v[232:235], v[96:111]
	v_mfma_f32_32x32x16_f16 v[80:95], v[200:203], v[224:227], v[80:95]
	v_mfma_f32_32x32x16_f16 v[64:79], v[200:203], v[232:235], v[64:79]
	v_mfma_f32_32x32x16_f16 v[48:63], v[208:211], v[224:227], v[48:63]
	v_mfma_f32_32x32x16_f16 v[32:47], v[208:211], v[232:235], v[32:47]
	v_mfma_f32_32x32x16_f16 v[16:31], v[216:219], v[224:227], v[16:31]
	v_mfma_f32_32x32x16_f16 v[0:15], v[216:219], v[232:235], v[0:15]
	s_setprio 0
	v_ashrrev_i32_e32 v128, 1, v169
	v_lshlrev_b32_e32 v130, 6, v169
	v_mul_lo_u32 v129, v128, s10
	v_and_b32_e32 v130, 64, v130
	v_lshl_add_u32 v133, v130, 2, v129
	v_add_u32_e32 v134, s4, v128
	v_or_b32_e32 v128, s5, v130
	v_readlane_b32 s4, v252, 2
	v_lshlrev_b32_e32 v130, 8, v167
	v_lshlrev_b32_e32 v152, 2, v128
	v_readlane_b32 s6, v252, 4
	v_readlane_b32 s7, v252, 5
	v_lshl_or_b32 v130, v168, 2, v130
	v_ashrrev_i32_e32 v132, 7, v169
	v_lshl_add_u64 v[128:129], s[6:7], 0, v[152:153]
	v_mad_u32_u24 v135, v166, s11, v130
	s_mov_b32 s14, 0
	s_mov_b64 s[6:7], -1
	v_readlane_b32 s5, v252, 3
	s_branch .LBB0_1004
